# attention queues: a wave served statically leaves the NA queue without polling (leftovers go to scan waves / waves without a static unit)
# speedup vs baseline: 1.0031x; 1.0031x over previous
; #define LAS __attribute__((address_space(3)))
; DI void na_wave_unit(KArgs args, LAS unsigned char* L, const Ctx& c, int u, int lane, int wave) {
;     const int l = c.layer, head = u & 3, gr = u >> 2, rows = c.seqlen >> 6, seq = gr / rows, r = gr % rows;
;     int rs = r - 4; rs = rs < 0 ? 0 : (rs > rows - 8 ? rows - 8 : rs);
;     const bf16_t* PROJ = BIGP(bf16_t, B_PROJ);
;     const size_t tq0 = (size_t)seq * c.seqlen + (size_t)r * 64;
;     LAS bf16_t* Vt = (LAS bf16_t*)(L + wave * WAREA);
;     LAS float* BIAS = (LAS float*)(L + wave * WAREA + 9216);
;     const int rr = lane & 31, hh = lane >> 5;
; #pragma unroll
;     for (int w = 0; w < 4; ++w) { const int idx = w * 64 + lane, kw = idx >> 5, dc = idx & 31;
;         if (dc < 31) BIAS[idx] = args->in[3][(((size_t)l * 4 + head) * 15 + (rs + kw - r + 7)) * 31 + dc]; }
;     bf16x8 qf[2][4];
; #pragma unroll
;     for (int nt = 0; nt < 2; ++nt)
; #pragma unroll
;         for (int ks = 0; ks < 4; ++ks) qf[nt][ks] = *(const bf16x8*)(PROJ + (tq0 + 32 * nt + rr) * NPROJ + C_QA + 64 * head + 16 * ks + 8 * hh);
;     f32x16 o[2][2]; o[0][0] = zero16(); o[0][1] = zero16(); o[1][0] = zero16(); o[1][1] = zero16();
;     float m[2] = {-1e30f, -1e30f}, ls[2] = {0.f, 0.f};
;     for (int w = 0; w < 8; ++w) {
;         const size_t tk0 = (size_t)seq * c.seqlen + (size_t)(rs + w) * 64;
;         u32x4 vr[8]; bf16x8 kf[2][4];
;         load_v(vr, lane, [&](int key) { return PROJ + (tk0 + key) * NPROJ + C_VA + 64 * head; });
; #pragma unroll
;         for (int mt = 0; mt < 2; ++mt)
; #pragma unroll
;             for (int ks = 0; ks < 4; ++ks) kf[mt][ks] = *(const bf16x8*)(PROJ + (tk0 + 32 * mt + rr) * NPROJ + C_KA + 64 * head + 16 * ks + 8 * hh);
;         __builtin_amdgcn_sched_barrier(0);
;         asm volatile("s_waitcnt lgkmcnt(0)" ::: "memory");
;         put_vt(Vt, lane, vr);
;         f32x16 acc[2][2]; acc[0][0] = zero16(); acc[0][1] = zero16(); acc[1][0] = zero16(); acc[1][1] = zero16();
; #pragma unroll
;         for (int mt = 0; mt < 2; ++mt)
; #pragma unroll
;             for (int ks = 0; ks < 4; ++ks) { acc[mt][0] = MFMA32(kf[mt][ks], qf[0][ks], acc[mt][0]); acc[mt][1] = MFMA32(kf[mt][ks], qf[1][ks], acc[mt][1]); }
;         asm volatile("s_waitcnt lgkmcnt(0)" ::: "memory");
;         const LAS float* brow = BIAS + w * 32;
; #pragma unroll
.LBB0_651:
	v_writelane_b32 v254, s31, 33
	s_lshl_b32 s0, s28, 7
	v_readlane_b32 s1, v254, 14
	s_or_b32 s92, s0, s1
	s_lshr_b32 s91, s29, 4
	s_lshl_b64 s[0:1], s[92:93], 2
	s_waitcnt lgkmcnt(0)
	s_add_u32 s0, s72, s0
	s_addc_u32 s1, s73, s1
	s_add_u32 s0, s0, 0x20000
	s_addc_u32 s1, s1, 0
	v_writelane_b32 v254, s0, 34
	v_mov_b32_e32 v2, v177
	s_nop 0
	v_writelane_b32 v254, s1, 35
	v_writelane_b32 v254, s30, 36
	s_add_i32 s0, s30, -8
	v_writelane_b32 v254, s0, 37
	s_add_u32 s6, s72, 0x18200000
	v_readlane_b32 s0, v254, 23
	s_addc_u32 s7, s73, 0
	v_readlane_b32 s1, v254, 24
	s_and_b64 s[0:1], s[0:1], exec
	s_cselect_b32 s0, 12, 14
	v_writelane_b32 v254, s0, 39
	s_add_u32 s0, s72, 0x32600000
	v_writelane_b32 v254, s72, 40
	s_addc_u32 s1, s73, 0
	v_and_b32_e32 v5, 63, v2
	v_writelane_b32 v254, s73, 41
	v_writelane_b32 v254, s0, 42
	v_lshlrev_b32_e32 v6, 3, v2
	v_lshlrev_b32_e32 v7, 2, v5
	v_writelane_b32 v254, s1, 43
	v_readfirstlane_b32 s0, v2
	s_lshr_b32 s0, s0, 6
	s_mulk_i32 s0, 0x2800
	s_add_i32 s1, s0, 0
	v_or_b32_e32 v4, 64, v5
	v_and_b32_e32 v6, 56, v6
	v_bfe_u32 v182, v2, 3, 3
	v_mov_b32_e32 v10, s1
	v_add_u32_e32 v179, s1, v7
	v_lshrrev_b32_e32 v183, 5, v4
	v_or_b32_e32 v4, 0x80, v5
	v_and_b32_e32 v8, 24, v7
	v_mad_u32_u24 v11, v6, s27, v10
	v_bitop3_b32 v7, v182, v7, 24 bitop3:0x72
	v_cmp_eq_u32_e64 s[2:3], 0, v5
	v_lshrrev_b32_e32 v185, 5, v4
	v_or_b32_e32 v4, 0xc0, v5
	v_or_b32_e32 v9, v8, v182
	v_lshl_add_u32 v195, v7, 1, v11
	v_bitop3_b32 v7, v182, v8, 40 bitop3:0x36
	v_or_b32_e32 v5, 32, v5
	v_lshl_add_u32 v189, v9, 1, v11
	v_bitop3_b32 v9, v182, v8, 8 bitop3:0x36
	v_lshl_add_u32 v197, v7, 1, v11
	v_bitop3_b32 v7, v182, v8, 48 bitop3:0x36
	v_lshrrev_b32_e32 v14, 1, v5
	v_and_b32_e32 v176, 31, v2
	v_lshl_add_u32 v191, v9, 1, v11
	v_bitop3_b32 v9, v182, v8, 16 bitop3:0x36
	v_lshl_add_u32 v226, v7, 1, v11
	v_bitop3_b32 v7, v182, v8, 56 bitop3:0x36
	v_and_b32_e32 v8, 4, v182
	v_and_b32_e32 v15, 24, v14
	v_mad_u32_u24 v12, v176, s27, v10
	v_mad_u32_u24 v10, v5, s27, v10
	v_or_b32_e32 v16, v15, v8
	v_bfe_u32 v1, v2, 5, 1
	v_lshl_add_u32 v193, v9, 1, v11
	v_or_b32_e32 v9, 16, v8
	v_lshrrev_b32_e32 v2, 1, v2
	v_lshl_add_u32 v230, v16, 1, v10
	v_bitop3_b32 v16, v15, 8, v8 bitop3:0x36
	v_lshl_add_u32 v231, v16, 1, v10
	v_bitop3_b32 v16, v9, 8, v2 bitop3:0x34
	v_bitop3_b32 v9, v14, v9, 24 bitop3:0x6c
	v_lshl_add_u32 v233, v9, 1, v10
	v_xor_b32_e32 v9, 8, v9
	v_lshl_add_u32 v234, v9, 1, v10
	v_or_b32_e32 v9, 32, v8
	v_lshl_add_u32 v232, v16, 1, v12
	v_bitop3_b32 v16, v9, 8, v2 bitop3:0x34
	v_bitop3_b32 v9, v15, 8, v9 bitop3:0x36
	v_and_or_b32 v13, v2, 8, v8
	v_lshl_add_u32 v236, v9, 1, v10
	v_or_b32_e32 v9, 48, v8
	v_lshl_add_u32 v228, v13, 1, v12
	v_bitop3_b32 v13, v8, 8, v2 bitop3:0x34
	v_bitop3_b32 v2, v9, 8, v2 bitop3:0x34
	v_lshl_add_u32 v237, v2, 1, v12
	v_bitop3_b32 v2, v14, v9, 24 bitop3:0x6c
	v_lshl_add_u32 v227, v7, 1, v11
	v_lshlrev_b32_e32 v7, 2, v1
	v_lshl_add_u32 v238, v2, 1, v10
	v_xor_b32_e32 v2, 8, v2
	v_lshl_add_u32 v239, v2, 1, v10
	v_sub_u32_e64 v9, v176, 8 clamp
	v_or_b32_e32 v10, 1, v7
	v_writelane_b32 v254, s2, 44
	v_cmp_lt_u32_e64 s[18:19], v10, v9
	v_or_b32_e32 v10, 2, v7
	v_writelane_b32 v254, s3, 45
	v_cmp_ne_u32_e64 s[2:3], 31, v176
	v_cmp_lt_u32_e64 s[20:21], v10, v9
	v_or_b32_e32 v10, 3, v7
	v_writelane_b32 v254, s2, 46
	v_cmp_lt_u32_e64 s[22:23], v10, v9
	v_or_b32_e32 v10, 8, v7
	v_writelane_b32 v254, s3, 47
	v_cmp_lt_u32_e64 s[2:3], v10, v9
	v_or_b32_e32 v10, 9, v7
	v_cmp_lt_u32_e64 s[4:5], v10, v9
	v_or_b32_e32 v10, 10, v7
	v_max_u32_e32 v2, 8, v176
	v_cmp_lt_u32_e64 s[30:31], v10, v9
	v_or_b32_e32 v10, 11, v7
	v_add_u32_e32 v2, 8, v2
	v_cmp_lt_u32_e64 s[34:35], v10, v9
	v_or_b32_e32 v10, 16, v7
	v_cmp_ge_u32_e32 vcc, v10, v9
	v_cmp_lt_u32_e64 s[24:25], v10, v2
	v_or_b32_e32 v10, 17, v7
	s_and_b64 s[36:37], vcc, s[24:25]
	v_cmp_ge_u32_e32 vcc, v10, v9
	v_cmp_lt_u32_e64 s[26:27], v10, v2
	v_or_b32_e32 v10, 18, v7
	s_mov_b64 s[24:25], s[2:3]
	s_and_b64 s[2:3], vcc, s[26:27]
	v_cmp_ge_u32_e32 vcc, v10, v9
	v_cmp_lt_u32_e64 s[28:29], v10, v2
	v_or_b32_e32 v10, 19, v7
	v_lshl_add_u32 v229, v13, 1, v12
	v_lshl_add_u32 v235, v16, 1, v12
; #define LAS __attribute__((address_space(3)))
; DI int crow(int reg, int h) { return (reg & 3) + 8 * (reg >> 2) + 4 * h; }
; DI void na_wave_unit(KArgs args, LAS unsigned char* L, const Ctx& c, int u, int lane, int wave) {
;     ...
;         for (int nt = 0; nt < 2; ++nt) { const int qc = 32 * nt + rr; int ws = qc - 8; ws = ws < 0 ? 0 : (ws > 48 ? 48 : ws);
; #pragma unroll
;             for (int mt = 0; mt < 2; ++mt) {
;                 const volatile LAS float* bp = brow + (32 * mt + 4 * hh - qc + 15); float bv[16];
; #pragma unroll
;                 for (int g = 0; g < 16; ++g) { const bool live = (mt == nt) || (nt == 0 ? g < 4 : g >= 12);
;                     bv[g] = live ? bp[(g & 3) + 8 * (g >> 2)] : 0.f; }
; #pragma unroll
;                 for (int g = 0; g < 16; ++g) { const bool live = (mt == nt) || (nt == 0 ? g < 4 : g >= 12); const int kc = 32 * mt + crow(g, hh); const bool ok = live && (kc >= ws) && (kc < ws + 16);
;                     acc[mt][nt][g] = ok ? acc[mt][nt][g] * 0.125f + bv[g] : -1e30f; } } }
; DI void attn_wave_units(KArgs args, LAS unsigned char* L, const Ctx& c) {
;     int tid = c.tid; asm volatile("" : "+v"(tid)); const int lane = tid & 63, wave = __builtin_amdgcn_readfirstlane(tid >> 6);
;     const int nch_ = c.stok >> 6, N_NA = nch_ * 4, N_DIL = nch_ * 6;
;     unsigned* q = (unsigned*)(c.ws + WS_CTL) + 32768 + 128 * (c.layer * 4 + c.slab);
;     for (;;) { unsigned u = 0; if (lane == 0) u = __hip_atomic_fetch_add(q, 1u, __ATOMIC_RELAXED, __HIP_MEMORY_SCOPE_AGENT);
;         u = (unsigned)__builtin_amdgcn_readfirstlane((int)u); if (u >= (unsigned)N_NA) break; na_wave_unit(args, L, c, (int)u, lane, wave); }
	v_cmp_lt_u32_e64 s[16:17], v7, v9
	s_and_b64 s[38:39], vcc, s[28:29]
	s_mov_b64 s[28:29], s[30:31]
	v_cmp_ge_u32_e32 vcc, v10, v9
	v_cmp_lt_u32_e64 s[30:31], v10, v2
	v_or_b32_e32 v9, 24, v7
	v_or_b32_e32 v10, 25, v7
	v_or_b32_e32 v12, 26, v7
	v_or_b32_e32 v14, 27, v7
	v_or_b32_e32 v15, 32, v7
	v_or_b32_e32 v16, 33, v7
	v_or_b32_e32 v17, 34, v7
	v_or_b32_e32 v18, 35, v7
	v_cmp_lt_u32_e64 s[42:43], v9, v2
	v_cmp_lt_u32_e64 s[44:45], v10, v2
	v_cmp_lt_u32_e64 s[46:47], v12, v2
	v_cmp_lt_u32_e64 s[48:49], v14, v2
	v_cmp_lt_u32_e64 s[50:51], v15, v2
	v_cmp_lt_u32_e64 s[52:53], v16, v2
	v_cmp_lt_u32_e64 s[54:55], v17, v2
	v_cmp_lt_u32_e64 s[56:57], v18, v2
	v_min_u32_e32 v2, 56, v5
	v_add_u32_e32 v19, -8, v2
	v_add_u32_e32 v20, 8, v2
	v_or_b32_e32 v2, 40, v7
	s_and_b64 s[40:41], vcc, s[30:31]
	v_cmp_ge_u32_e32 vcc, v2, v19
	v_cmp_lt_u32_e64 s[66:67], v2, v20
	v_or_b32_e32 v2, 41, v7
	s_mov_b64 s[30:31], s[34:35]
	s_mov_b64 s[34:35], s[36:37]
	s_mov_b64 s[36:37], s[2:3]
	v_cmp_lt_u32_e64 s[2:3], v15, v19
	s_and_b64 s[76:77], vcc, s[66:67]
	v_cmp_ge_u32_e32 vcc, v2, v19
	v_cmp_lt_u32_e64 s[68:69], v2, v20
	v_or_b32_e32 v2, 42, v7
	v_cmp_lt_u32_e64 s[72:73], v17, v19
	s_mov_b64 s[66:67], s[2:3]
	s_and_b64 s[2:3], vcc, s[68:69]
	v_cmp_ge_u32_e32 vcc, v2, v19
	v_cmp_lt_u32_e64 s[70:71], v2, v20
	v_or_b32_e32 v2, 43, v7
	s_and_b64 s[78:79], vcc, s[70:71]
	s_mov_b64 s[70:71], s[72:73]
	v_cmp_ge_u32_e32 vcc, v2, v19
	v_cmp_lt_u32_e64 s[72:73], v2, v20
	v_or_b32_e32 v2, 48, v7
	v_cmp_lt_u32_e64 s[82:83], v2, v20
	v_or_b32_e32 v2, 49, v7
	v_cmp_lt_u32_e64 s[84:85], v2, v20
	v_lshlrev_b32_e32 v2, 4, v1
	v_mul_u32_u24_e32 v13, 0x90, v5
	v_lshl_add_u64 v[198:199], s[6:7], 0, v[2:3]
	v_or_b32_e32 v2, s0, v2
	v_lshlrev_b32_e32 v5, 2, v5
	v_sub_u32_e32 v5, v2, v5
	v_readlane_b32 s0, v253, 55
	s_mov_b64 s[26:27], s[4:5]
	v_cmp_lt_u32_e64 s[60:61], v10, v19
	v_add_u32_e32 v240, s0, v5
	v_lshlrev_b32_e32 v5, 2, v176
	v_cmp_lt_u32_e64 s[4:5], v16, v19
	v_lshl_add_u32 v10, v8, 1, s1
	v_lshlrev_b32_e32 v8, 1, v6
	v_or_b32_e32 v16, 56, v7
	v_sub_u32_e32 v2, v2, v5
	v_readlane_b32 s0, v253, 56
	v_cmp_lt_u32_e64 s[62:63], v12, v19
	v_add_u32_e32 v12, s1, v8
	v_add_u32_e32 v241, s0, v2
	v_cmp_lt_u32_e64 s[0:1], v16, v20
	v_or_b32_e32 v17, 57, v7
	v_cmp_lt_u32_e64 s[74:75], v18, v19
	v_writelane_b32 v254, s0, 48
	v_or_b32_e32 v18, 58, v7
	v_cmp_lt_u32_e64 s[64:65], v14, v19
	v_writelane_b32 v254, s1, 49
	v_cmp_lt_u32_e64 s[0:1], v17, v20
	v_or_b32_e32 v14, 50, v7
	v_or_b32_e32 v15, 51, v7
	v_writelane_b32 v254, s0, 50
	v_or_b32_e32 v7, 59, v7
	v_lshrrev_b32_e32 v187, 5, v4
	v_writelane_b32 v254, s1, 51
	v_cmp_lt_u32_e64 s[0:1], v18, v20
	v_lshlrev_b32_e32 v4, 3, v1
	v_mul_u32_u24_e32 v11, 0x90, v176
	v_writelane_b32 v254, s0, 52
	v_cmp_lt_u32_e64 s[58:59], v9, v19
	v_mul_u32_u24_e32 v19, 0x90, v182
	v_writelane_b32 v254, s1, 53
	v_cmp_lt_u32_e64 s[0:1], v7, v20
	v_mov_b32_e32 v9, v3
	v_or_b32_e32 v184, 8, v182
	v_writelane_b32 v254, s0, 54
	v_or_b32_e32 v186, 16, v182
	v_or_b32_e32 v188, 24, v182
	v_or_b32_e32 v190, 32, v182
	v_or_b32_e32 v192, 40, v182
	v_or_b32_e32 v194, 48, v182
	v_or_b32_e32 v196, 56, v182
	s_mov_b64 s[68:69], s[4:5]
	s_and_b64 s[80:81], vcc, s[72:73]
	s_mov_b64 s[72:73], s[74:75]
	s_mov_b64 s[74:75], s[76:77]
	s_mov_b64 s[76:77], s[2:3]
	v_lshl_add_u64 v[200:201], s[6:7], 0, v[8:9]
	v_lshlrev_b32_e32 v2, 1, v4
	v_add_u32_e32 v242, v10, v11
	v_add_u32_e32 v243, v10, v13
	v_add_u32_e32 v244, v12, v19
	v_lshlrev_b32_e32 v202, 1, v6
	v_cmp_lt_u32_e64 s[86:87], v14, v20
	v_cmp_lt_u32_e64 s[88:89], v15, v20
	v_writelane_b32 v254, s1, 55
	v_readfirstlane_b32 s0, v0
	s_nop 1
	s_lshr_b32 s0, s0, 6
	v_readlane_b32 s1, v253, 59
	s_nop 1
	s_lshl_b32 s2, s1, 3
	s_add_i32 s2, s2, s0
	v_readlane_b32 s4, v254, 23
	v_readlane_b32 s5, v254, 24
	s_nop 1
	s_and_b64 s[4:5], s[4:5], exec
	s_cselect_b32 s3, 0xc0, 24
	s_cmp_lt_u32 s1, s3
	s_cselect_b32 s3, 1, 0
	s_cmp_eq_u32 s0, 0
	s_cselect_b32 s0, s3, 0
	s_cmp_lg_u32 s0, 0
	s_cbranch_scc1 .LBB0_653
	s_cmp_ge_u32 s2, s91
	s_cbranch_scc1 .LBB0_653
	s_mov_b32 s0, 1
	v_writelane_b32 v255, s0, 63
	s_branch .Lna_body

; DI void attn_wave_units(KArgs args, LAS unsigned char* L, const Ctx& c) {
;     ...
;     for (;;) { unsigned u = 0; if (lane == 0) u = __hip_atomic_fetch_add(q, 1u, __ATOMIC_RELAXED, __HIP_MEMORY_SCOPE_AGENT);
;         u = (unsigned)__builtin_amdgcn_readfirstlane((int)u); if (u >= (unsigned)N_NA) break; na_wave_unit(args, L, c, (int)u, lane, wave); }
.LBB0_657:
	s_or_b64 exec, exec, s[2:3]
	v_readfirstlane_b32 s2, v4
	v_readlane_b32 s0, v254, 23
	v_readlane_b32 s1, v254, 24
	s_nop 1
	s_and_b64 s[0:1], s[0:1], exec
	s_cselect_b32 s3, 0xc0, 24
	s_cselect_b32 s4, 0, 0x80
	v_readlane_b32 s5, v254, 2
	s_nop 1
	s_lshl_b32 s5, s5, 3
	s_sub_u32 s0, s91, s5
	s_cselect_b32 s0, 0, s0
	s_add_i32 s0, s0, s3
	s_add_i32 s0, s0, s4
	s_cmp_ge_u32 s2, s0
	s_mov_b64 s[0:1], -1
	s_cbranch_scc1 .LBB0_652
	s_mov_b32 s0, 0
	v_writelane_b32 v255, s0, 63
	s_cmp_lt_u32 s2, s3
	s_cbranch_scc1 .Lna_map_scan
	s_sub_i32 s2, s2, s3
	s_cmp_lt_u32 s2, s4
	s_cbranch_scc1 .Lna_map_sel
	s_sub_i32 s2, s2, s4
	s_add_i32 s2, s2, s5
	s_branch .Lna_body

; #define MFMA32(a, b, c) __builtin_amdgcn_mfma_f32_32x32x16_bf16((a), (b), (c), 0, 0, 0)
; DI f32x16 zero16() { f32x16 z; for (int i = 0; i < 16; ++i) z[i] = 0.f; return z; }
; DI void na_wave_unit(KArgs args, LAS unsigned char* L, const Ctx& c, int u, int lane, int wave) {
;     ...
;     for (int w = 0; w < 8; ++w) {
;         const size_t tk0 = (size_t)seq * c.seqlen + (size_t)(rs + w) * 64;
;         u32x4 vr[8]; bf16x8 kf[2][4];
;         load_v(vr, lane, [&](int key) { return PROJ + (tk0 + key) * NPROJ + C_VA + 64 * head; });
; #pragma unroll
;         for (int mt = 0; mt < 2; ++mt)
; #pragma unroll
;             for (int ks = 0; ks < 4; ++ks) kf[mt][ks] = *(const bf16x8*)(PROJ + (tk0 + 32 * mt + rr) * NPROJ + C_KA + 64 * head + 16 * ks + 8 * hh);
;         __builtin_amdgcn_sched_barrier(0);
;         asm volatile("s_waitcnt lgkmcnt(0)" ::: "memory");
;         put_vt(Vt, lane, vr);
;         f32x16 acc[2][2]; acc[0][0] = zero16(); acc[0][1] = zero16(); acc[1][0] = zero16(); acc[1][1] = zero16();
; #pragma unroll
;         for (int mt = 0; mt < 2; ++mt)
; #pragma unroll
;             for (int ks = 0; ks < 4; ++ks) { acc[mt][0] = MFMA32(kf[mt][ks], qf[0][ks], acc[mt][0]); acc[mt][1] = MFMA32(kf[mt][ks], qf[1][ks], acc[mt][1]); }
.LBB0_661:
	s_ashr_i32 s3, s2, 31
	s_lshl_b64 vcc, s[2:3], 6
	s_add_u32 s3, vcc_lo, s94
	v_or_b32_e32 v68, s3, v182
	s_addc_u32 s5, vcc_hi, s95
	v_mad_u64_u32 v[72:73], vcc, v68, s90, v[204:205]
	v_or_b32_e32 v68, s3, v184
	v_mad_u64_u32 v[76:77], vcc, v68, s90, v[204:205]
	v_or_b32_e32 v68, s3, v186
	v_mad_u64_u32 v[80:81], vcc, v68, s90, v[204:205]
	v_or_b32_e32 v68, s3, v188
	s_waitcnt vmcnt(0)
	v_mad_u64_u32 v[100:101], vcc, v68, s90, v[204:205]
	v_or_b32_e32 v68, s3, v190
	v_mad_u64_u32 v[104:105], vcc, v68, s90, v[204:205]
	v_or_b32_e32 v68, s3, v192
	v_mad_u64_u32 v[108:109], vcc, v68, s90, v[204:205]
	v_or_b32_e32 v68, s3, v194
	v_mad_u64_u32 v[112:113], vcc, v68, s90, v[204:205]
	v_or_b32_e32 v68, s3, v196
	v_mad_u64_u32 v[116:117], vcc, v68, s90, v[204:205]
	v_or_b32_e32 v70, s3, v176
	v_mov_b64_e32 v[68:69], s[6:7]
	v_mad_u64_u32 v[68:69], vcc, v70, s90, v[68:69]
	v_mad_i32_i24 v69, s5, v223, v69
	s_lshl_b32 s92, s33, 1
	v_lshl_add_u64 v[68:69], v[68:69], 0, s[92:93]
	v_lshl_add_u64 v[74:75], v[68:69], 0, v[2:3]
	s_mov_b64 vcc, 0x38200
	global_load_dwordx4 v[68:71], v[74:75], off offset:512
	global_load_dwordx4 v[88:91], v[74:75], off offset:544
	global_load_dwordx4 v[92:95], v[74:75], off offset:576
	global_load_dwordx4 v[96:99], v[74:75], off offset:608
	v_lshl_add_u64 v[78:79], v[74:75], 0, vcc
	v_add_co_u32_e32 v74, vcc, s0, v74
	v_mad_i32_i24 v73, s5, v223, v73
	v_mad_i32_i24 v77, s5, v223, v77
	v_mad_i32_i24 v81, s5, v223, v81
	v_mad_i32_i24 v101, s5, v223, v101
	v_mad_i32_i24 v105, s5, v223, v105
	v_mad_i32_i24 v109, s5, v223, v109
	v_mad_i32_i24 v113, s5, v223, v113
	v_mad_i32_i24 v117, s5, v223, v117
	v_addc_co_u32_e32 v75, vcc, 0, v75, vcc
	global_load_dwordx4 v[172:175], v[78:79], off offset:32
	global_load_dwordx4 v[164:167], v[78:79], off offset:64
	global_load_dwordx4 v[84:87], v[74:75], off offset:512
	global_load_dwordx4 v[168:171], v[78:79], off offset:96
	s_nop 0
	global_load_dwordx4 v[72:75], v[72:73], off offset:1024
	s_nop 0
	global_load_dwordx4 v[76:79], v[76:77], off offset:1024
	s_nop 0
	global_load_dwordx4 v[80:83], v[80:81], off offset:1024
	s_nop 0
	global_load_dwordx4 v[100:103], v[100:101], off offset:1024
	s_nop 0
	global_load_dwordx4 v[104:107], v[104:105], off offset:1024
	s_nop 0
	global_load_dwordx4 v[108:111], v[108:109], off offset:1024
	s_nop 0
	global_load_dwordx4 v[112:115], v[112:113], off offset:1024
	s_nop 0
	global_load_dwordx4 v[116:119], v[116:117], off offset:1024
	s_waitcnt lgkmcnt(0)
	s_waitcnt vmcnt(7)
	ds_write_b16 v189, v72
	ds_write_b16_d16_hi v189, v72 offset:144
	ds_write_b16 v189, v73 offset:288
	ds_write_b16_d16_hi v189, v73 offset:432
	ds_write_b16 v189, v74 offset:576
	ds_write_b16_d16_hi v189, v74 offset:720
	ds_write_b16 v189, v75 offset:864
	ds_write_b16_d16_hi v189, v75 offset:1008
	s_waitcnt vmcnt(6)
	ds_write_b16 v191, v76
	ds_write_b16_d16_hi v191, v76 offset:144
	ds_write_b16 v191, v77 offset:288
	ds_write_b16_d16_hi v191, v77 offset:432
	ds_write_b16 v191, v78 offset:576
	ds_write_b16_d16_hi v191, v78 offset:720
	ds_write_b16 v191, v79 offset:864
	ds_write_b16_d16_hi v191, v79 offset:1008
	s_waitcnt vmcnt(5)
	ds_write_b16 v193, v80
	ds_write_b16_d16_hi v193, v80 offset:144
	ds_write_b16 v193, v81 offset:288
	ds_write_b16_d16_hi v193, v81 offset:432
	ds_write_b16 v193, v82 offset:576
	ds_write_b16_d16_hi v193, v82 offset:720
	ds_write_b16 v193, v83 offset:864
	ds_write_b16_d16_hi v193, v83 offset:1008
	s_waitcnt vmcnt(4)
	ds_write_b16 v195, v100
	ds_write_b16_d16_hi v195, v100 offset:144
	ds_write_b16 v195, v101 offset:288
	ds_write_b16_d16_hi v195, v101 offset:432
	ds_write_b16 v195, v102 offset:576
	ds_write_b16_d16_hi v195, v102 offset:720
	ds_write_b16 v195, v103 offset:864
	ds_write_b16_d16_hi v195, v103 offset:1008
	s_waitcnt vmcnt(3)
	ds_write_b16 v189, v104 offset:64
	ds_write_b16_d16_hi v189, v104 offset:208
	ds_write_b16 v189, v105 offset:352
	ds_write_b16_d16_hi v189, v105 offset:496
	ds_write_b16 v189, v106 offset:640
	ds_write_b16_d16_hi v189, v106 offset:784
	ds_write_b16 v189, v107 offset:928
	ds_write_b16_d16_hi v189, v107 offset:1072
	s_waitcnt vmcnt(2)
	ds_write_b16 v197, v108
	ds_write_b16_d16_hi v197, v108 offset:144
	ds_write_b16 v197, v109 offset:288
	ds_write_b16_d16_hi v197, v109 offset:432
	ds_write_b16 v197, v110 offset:576
	ds_write_b16_d16_hi v197, v110 offset:720
	ds_write_b16 v197, v111 offset:864
	ds_write_b16_d16_hi v197, v111 offset:1008
	s_waitcnt vmcnt(1)
	ds_write_b16 v226, v112
	ds_write_b16_d16_hi v226, v112 offset:144
	ds_write_b16 v226, v113 offset:288
	ds_write_b16_d16_hi v226, v113 offset:432
	ds_write_b16 v226, v114 offset:576
	ds_write_b16_d16_hi v226, v114 offset:720
	ds_write_b16 v226, v115 offset:864
	ds_write_b16_d16_hi v226, v115 offset:1008
	s_waitcnt vmcnt(0)
	ds_write_b16 v227, v116
	ds_write_b16_d16_hi v227, v116 offset:144
	ds_write_b16 v227, v117 offset:288
	ds_write_b16_d16_hi v227, v117 offset:432
	ds_write_b16 v227, v118 offset:576
	ds_write_b16_d16_hi v227, v118 offset:720
	ds_write_b16 v227, v119 offset:864
	ds_write_b16_d16_hi v227, v119 offset:1008
	v_mfma_f32_32x32x16_bf16 v[100:115], v[68:71], v[132:135], 0
	s_waitcnt lgkmcnt(0)
; #define LAS __attribute__((address_space(3)))
; #define MFMA32(a, b, c) __builtin_amdgcn_mfma_f32_32x32x16_bf16((a), (b), (c), 0, 0, 0)
; DI int crow(int reg, int h) { return (reg & 3) + 8 * (reg >> 2) + 4 * h; }
; DI void osm_update(f32x16 (&acc)[2][2], f32x16 (&o)[2][2], float (&m)[2], float (&l)[2]) {
;     ...
;     for (int nt = 0; nt < 2; ++nt) { float mx = -1e30f;
; #pragma unroll
;         for (int mt = 0; mt < 2; ++mt)
; #pragma unroll
;             for (int g = 0; g < 16; ++g) mx = fmaxf(mx, acc[mt][nt][g]);
;         mx = fmaxf(mx, __shfl_xor(mx, 32));
; DI void na_wave_unit(KArgs args, LAS unsigned char* L, const Ctx& c, int u, int lane, int wave) {
;     ...
; #pragma unroll
;         for (int mt = 0; mt < 2; ++mt)
; #pragma unroll
;             for (int ks = 0; ks < 4; ++ks) { acc[mt][0] = MFMA32(kf[mt][ks], qf[0][ks], acc[mt][0]); acc[mt][1] = MFMA32(kf[mt][ks], qf[1][ks], acc[mt][1]); }
;         asm volatile("s_waitcnt lgkmcnt(0)" ::: "memory");
;         const LAS float* brow = BIAS + w * 32;
; #pragma unroll
;         for (int nt = 0; nt < 2; ++nt) { const int qc = 32 * nt + rr; int ws = qc - 8; ws = ws < 0 ? 0 : (ws > 48 ? 48 : ws);
; #pragma unroll
;             for (int mt = 0; mt < 2; ++mt) {
;                 const volatile LAS float* bp = brow + (32 * mt + 4 * hh - qc + 15); float bv[16];
; #pragma unroll
;                 for (int g = 0; g < 16; ++g) { const bool live = (mt == nt) || (nt == 0 ? g < 4 : g >= 12);
;                     bv[g] = live ? bp[(g & 3) + 8 * (g >> 2)] : 0.f; }
; #pragma unroll
;                 for (int g = 0; g < 16; ++g) { const bool live = (mt == nt) || (nt == 0 ? g < 4 : g >= 12); const int kc = 32 * mt + crow(g, hh); const bool ok = live && (kc >= ws) && (kc < ws + 16);
;                     acc[mt][nt][g] = ok ? acc[mt][nt][g] * 0.125f + bv[g] : -1e30f; } } }
	s_add_i32 s2, s2, 1
	v_mfma_f32_32x32x16_bf16 v[68:83], v[68:71], v[148:151], 0
	v_mfma_f32_32x32x16_bf16 v[100:115], v[88:91], v[136:139], v[100:115]
	v_mfma_f32_32x32x16_bf16 v[68:83], v[88:91], v[152:155], v[68:83]
	v_mfma_f32_32x32x16_bf16 v[116:131], v[84:87], v[132:135], 0
	v_mfma_f32_32x32x16_bf16 v[100:115], v[92:95], v[140:143], v[100:115]
	v_mfma_f32_32x32x16_bf16 v[68:83], v[92:95], v[156:159], v[68:83]
	v_mfma_f32_32x32x16_bf16 v[116:131], v[172:175], v[136:139], v[116:131]
	v_mfma_f32_32x32x16_bf16 v[100:115], v[96:99], v[144:147], v[100:115]
	v_mfma_f32_32x32x16_bf16 v[68:83], v[96:99], v[160:163], v[68:83]
	v_mfma_f32_32x32x16_bf16 v[84:99], v[84:87], v[148:151], 0
	s_nop 10
	v_add_u32_e32 v68, s4, v241
	v_mfma_f32_32x32x16_bf16 v[116:131], v[164:167], v[140:143], v[116:131]
	v_mfma_f32_32x32x16_bf16 v[84:99], v[172:175], v[152:155], v[84:99]
	v_mfma_f32_32x32x16_bf16 v[116:131], v[168:171], v[144:147], v[116:131]
	ds_read_b32 v69, v68
	ds_read_b32 v70, v68 offset:4
	ds_read_b32 v71, v68 offset:8
	ds_read_b32 v72, v68 offset:12
	ds_read_b32 v73, v68 offset:32
	ds_read_b32 v74, v68 offset:36
	ds_read_b32 v75, v68 offset:40
	ds_read_b32 v76, v68 offset:44
	ds_read_b32 v77, v68 offset:64
	ds_read_b32 v78, v68 offset:68
	s_nop 1
	ds_read_b32 v124, v68 offset:72
	ds_read_b32 v125, v68 offset:76
	ds_read_b32 v126, v68 offset:96
	ds_read_b32 v127, v68 offset:100
	ds_read_b32 v128, v68 offset:104
	ds_read_b32 v129, v68 offset:108
	s_waitcnt lgkmcnt(14)
	v_fmac_f32_e32 v70, 0x3e000000, v101
	s_waitcnt lgkmcnt(12)
	v_fmac_f32_e32 v72, 0x3e000000, v103
	v_cndmask_b32_e64 v122, v70, v224, s[18:19]
	v_cndmask_b32_e64 v120, v72, v224, s[22:23]
	s_waitcnt lgkmcnt(10)
	v_fmac_f32_e32 v74, 0x3e000000, v105
	ds_read_b32 v70, v68 offset:128
	ds_read_b32 v72, v68 offset:132
	ds_read_b32 v105, v68 offset:136
	ds_read_b32 v68, v68 offset:140
	v_mfma_f32_32x32x16_bf16 v[84:99], v[164:167], v[156:159], v[84:99]
	s_waitcnt lgkmcnt(12)
	v_fmac_f32_e32 v76, 0x3e000000, v107
	s_waitcnt lgkmcnt(3)
	v_fmac_f32_e32 v70, 0x3e000000, v116
	v_cndmask_b32_e64 v101, v76, v224, s[30:31]
	s_waitcnt lgkmcnt(0)
	v_fmac_f32_e32 v68, 0x3e000000, v119
	v_cndmask_b32_e64 v76, v224, v70, s[50:51]
	v_fmac_f32_e32 v72, 0x3e000000, v117
	v_fmac_f32_e32 v105, 0x3e000000, v118
	v_cndmask_b32_e64 v70, v224, v68, s[56:57]
	v_add_u32_e32 v68, s4, v240
	v_cndmask_b32_e64 v103, v74, v224, s[26:27]
	v_fmac_f32_e32 v75, 0x3e000000, v106
	v_fmac_f32_e32 v77, 0x3e000000, v108
	v_cndmask_b32_e64 v74, v224, v72, s[52:53]
	v_cndmask_b32_e64 v72, v224, v105, s[54:55]
	ds_read_b32 v105, v68
	ds_read_b32 v106, v68 offset:4
	ds_read_b32 v107, v68 offset:8
	ds_read_b32 v108, v68 offset:12
	v_mfma_f32_32x32x16_bf16 v[84:99], v[168:171], v[160:163], v[84:99]
	s_waitcnt lgkmcnt(3)
	v_fmac_f32_e32 v105, 0x3e000000, v80
	v_fmac_f32_e32 v78, 0x3e000000, v109
	s_waitcnt lgkmcnt(1)
	v_fmac_f32_e32 v107, 0x3e000000, v82
	s_waitcnt lgkmcnt(0)
	v_fmac_f32_e32 v108, 0x3e000000, v83
	v_fmac_f32_e32 v124, 0x3e000000, v110
	v_fmac_f32_e32 v125, 0x3e000000, v111
	v_fmac_f32_e32 v126, 0x3e000000, v112
	v_fmac_f32_e32 v127, 0x3e000000, v113
	v_fmac_f32_e32 v128, 0x3e000000, v114
	v_fmac_f32_e32 v129, 0x3e000000, v115
	v_cndmask_b32_e64 v110, v105, v224, s[58:59]
	v_fmac_f32_e32 v106, 0x3e000000, v81
	v_cndmask_b32_e64 v112, v107, v224, s[62:63]
	v_cndmask_b32_e64 v114, v108, v224, s[64:65]
	ds_read_b32 v80, v68 offset:32
	ds_read_b32 v81, v68 offset:36
	ds_read_b32 v82, v68 offset:40
	ds_read_b32 v83, v68 offset:44
	ds_read_b32 v105, v68 offset:64
	ds_read_b32 v107, v68 offset:68
	ds_read_b32 v108, v68 offset:72
	ds_read_b32 v109, v68 offset:76
	ds_read_b32 v111, v68 offset:96
	ds_read_b32 v113, v68 offset:100
	ds_read_b32 v115, v68 offset:104
	ds_read_b32 v116, v68 offset:108
	ds_read_b32 v117, v68 offset:128
	ds_read_b32 v118, v68 offset:132
	ds_read_b32 v119, v68 offset:136
	ds_read_b32 v68, v68 offset:140
	s_waitcnt lgkmcnt(14)
	v_fmac_f32_e32 v80, 0x3e000000, v84
	v_cndmask_b32_e64 v79, v224, v78, s[36:37]
	v_cndmask_b32_e64 v78, v224, v124, s[38:39]
	v_cndmask_b32_e64 v124, v80, v224, s[66:67]
	s_waitcnt lgkmcnt(0)
	v_fmac_f32_e32 v68, 0x3e000000, v99
	v_and_b32_e32 v80, 64, v212
	v_cndmask_b32_e64 v173, v224, v68, s[12:13]
	v_xor_b32_e32 v68, 32, v212
	v_add_u32_e32 v80, 64, v80
	v_fmac_f32_e32 v69, 0x3e000000, v100
	v_cmp_lt_i32_e32 vcc, v68, v80
	v_cndmask_b32_e64 v123, v69, v224, s[16:17]
	v_fmac_f32_e32 v71, 0x3e000000, v102
	v_cndmask_b32_e32 v68, v212, v68, vcc
	v_cndmask_b32_e64 v121, v71, v224, s[20:21]
	v_fmac_f32_e32 v73, 0x3e000000, v104
	v_lshlrev_b32_e32 v178, 2, v68
	v_max_f32_e32 v68, 0xf149f2ca, v123
	v_cndmask_b32_e64 v104, v73, v224, s[24:25]
	v_max3_f32 v68, v68, v122, v121
	v_cndmask_b32_e64 v102, v75, v224, s[28:29]
	v_max3_f32 v68, v68, v120, v104
	v_cndmask_b32_e64 v100, v224, v77, s[34:35]
	v_max3_f32 v68, v68, v103, v102
	v_max3_f32 v68, v68, v101, v100
	v_cndmask_b32_e64 v77, v224, v125, s[40:41]
	v_cndmask_b32_e64 v75, v224, v126, s[42:43]
	v_max3_f32 v68, v68, v79, v78
	v_cndmask_b32_e64 v73, v224, v127, s[44:45]
	v_cndmask_b32_e64 v71, v224, v128, s[46:47]
	v_max3_f32 v68, v68, v77, v75
	v_cndmask_b32_e64 v69, v224, v129, s[48:49]
	v_max3_f32 v68, v68, v73, v71
	v_max3_f32 v68, v68, v69, v76
	v_max3_f32 v68, v68, v74, v72
	v_max3_f32 v68, v68, v70, s1
	ds_bpermute_b32 v80, v178, v68
	v_fmac_f32_e32 v111, 0x3e000000, v92
	v_cndmask_b32_e64 v164, v224, v111, s[82:83]
	v_fmac_f32_e32 v113, 0x3e000000, v93
	v_cndmask_b32_e64 v165, v224, v113, s[84:85]
	s_waitcnt lgkmcnt(0)
; DI void osm_update(f32x16 (&acc)[2][2], f32x16 (&o)[2][2], float (&m)[2], float (&l)[2]) {
; #pragma unroll
;     for (int nt = 0; nt < 2; ++nt) { float mx = -1e30f;
; #pragma unroll
;         for (int mt = 0; mt < 2; ++mt)
; #pragma unroll
;             for (int g = 0; g < 16; ++g) mx = fmaxf(mx, acc[mt][nt][g]);
;         mx = fmaxf(mx, __shfl_xor(mx, 32));
;         const float mn = fmaxf(m[nt], mx), sc = __expf(m[nt] - mn); float sm = 0.f;
; #pragma unroll
;         for (int mt = 0; mt < 2; ++mt)
; #pragma unroll
;             for (int g = 0; g < 16; ++g) { const float pz = __expf(acc[mt][nt][g] - mn); acc[mt][nt][g] = pz; sm += pz; }
;         sm += __shfl_xor(sm, 32);
;         l[nt] = l[nt] * sc + sm; m[nt] = mn;
; #pragma unroll
;         for (int g = 0; g < 16; ++g) { o[0][nt][g] *= sc; o[1][nt][g] *= sc; } }
	v_max3_f32 v68, v245, v68, v80
	v_sub_f32_e32 v69, v69, v68
	v_mul_f32_e32 v69, 0x3fb8aa3b, v69
	v_exp_f32_e32 v111, v69
	v_sub_f32_e32 v69, v76, v68
	v_mul_f32_e32 v69, 0x3fb8aa3b, v69
	v_exp_f32_e32 v113, v69
	v_sub_f32_e32 v69, v74, v68
	v_fmac_f32_e32 v115, 0x3e000000, v94
	v_mul_f32_e32 v69, 0x3fb8aa3b, v69
	v_cndmask_b32_e64 v166, v224, v115, s[86:87]
	v_exp_f32_e32 v115, v69
	v_sub_f32_e32 v69, v72, v68
	v_fmac_f32_e32 v117, 0x3e000000, v96
	v_mul_f32_e32 v69, 0x3fb8aa3b, v69
	v_cndmask_b32_e64 v168, v224, v117, s[14:15]
	v_exp_f32_e32 v117, v69
	v_sub_f32_e32 v69, v70, v68
	v_fmac_f32_e32 v82, 0x3e000000, v86
	v_fmac_f32_e32 v119, 0x3e000000, v98
	v_mul_f32_e32 v69, 0x3fb8aa3b, v69
	v_cndmask_b32_e64 v126, v82, v224, s[70:71]
	v_cndmask_b32_e64 v171, v224, v119, s[8:9]
	v_sub_f32_e32 v82, v122, v68
	v_exp_f32_e32 v119, v69
	v_sub_f32_e32 v69, 0xf149f2ca, v68
	v_cndmask_b32_e64 v106, v106, v224, s[60:61]
	v_fmac_f32_e32 v83, 0x3e000000, v87
	v_mul_f32_e32 v82, 0x3fb8aa3b, v82
	v_mul_f32_e32 v69, 0x3fb8aa3b, v69
	v_fmac_f32_e32 v81, 0x3e000000, v85
	v_cndmask_b32_e64 v127, v83, v224, s[72:73]
	v_exp_f32_e32 v83, v82
	v_sub_f32_e32 v82, v121, v68
	v_exp_f32_e32 v121, v69
	v_max3_f32 v69, v110, s1, v106
	v_cndmask_b32_e64 v125, v81, v224, s[68:69]
	v_max3_f32 v69, v69, v112, v114
	v_fmac_f32_e32 v105, 0x3e000000, v88
	v_fmac_f32_e32 v107, 0x3e000000, v89
	v_max3_f32 v69, v69, v124, v125
	v_cndmask_b32_e64 v128, v224, v105, s[74:75]
	v_cndmask_b32_e64 v129, v224, v107, s[76:77]
	v_fmac_f32_e32 v108, 0x3e000000, v90
	v_fmac_f32_e32 v109, 0x3e000000, v91
	v_max3_f32 v69, v69, v126, v127
	v_cndmask_b32_e64 v130, v224, v108, s[78:79]
	v_cndmask_b32_e64 v131, v224, v109, s[80:81]
	v_sub_f32_e32 v80, v245, v68
	v_max3_f32 v69, v69, v128, v129
	v_fmac_f32_e32 v116, 0x3e000000, v95
	v_mul_f32_e32 v80, 0x3fb8aa3b, v80
	v_max3_f32 v69, v69, v130, v131
	v_cndmask_b32_e64 v167, v224, v116, s[88:89]
	v_fmac_f32_e32 v118, 0x3e000000, v97
	v_exp_f32_e32 v70, v80
	v_max3_f32 v69, v69, v164, v165
	v_cndmask_b32_e64 v169, v224, v118, s[10:11]
	v_max3_f32 v69, v69, v166, v167
	v_sub_f32_e32 v71, v71, v68
	v_max3_f32 v69, v69, v168, v169
	v_mul_f32_e32 v71, 0x3fb8aa3b, v71
	v_max3_f32 v69, v69, v171, v173
	v_exp_f32_e32 v109, v71
	v_pk_mul_f32 v[66:67], v[66:67], v[70:71] op_sel_hi:[1,0]
	v_pk_mul_f32 v[64:65], v[64:65], v[70:71] op_sel_hi:[1,0]
	v_pk_mul_f32 v[62:63], v[62:63], v[70:71] op_sel_hi:[1,0]
	v_pk_mul_f32 v[60:61], v[60:61], v[70:71] op_sel_hi:[1,0]
	v_pk_mul_f32 v[58:59], v[58:59], v[70:71] op_sel_hi:[1,0]
	v_pk_mul_f32 v[56:57], v[56:57], v[70:71] op_sel_hi:[1,0]
	v_pk_mul_f32 v[54:55], v[54:55], v[70:71] op_sel_hi:[1,0]
	v_pk_mul_f32 v[52:53], v[52:53], v[70:71] op_sel_hi:[1,0]
	v_pk_mul_f32 v[34:35], v[34:35], v[70:71] op_sel_hi:[1,0]
	v_pk_mul_f32 v[32:33], v[32:33], v[70:71] op_sel_hi:[1,0]
	v_pk_mul_f32 v[30:31], v[30:31], v[70:71] op_sel_hi:[1,0]
	v_pk_mul_f32 v[28:29], v[28:29], v[70:71] op_sel_hi:[1,0]
	v_pk_mul_f32 v[26:27], v[26:27], v[70:71] op_sel_hi:[1,0]
	v_pk_mul_f32 v[24:25], v[24:25], v[70:71] op_sel_hi:[1,0]
	v_pk_mul_f32 v[22:23], v[22:23], v[70:71] op_sel_hi:[1,0]
	v_pk_mul_f32 v[20:21], v[20:21], v[70:71] op_sel_hi:[1,0]
	ds_bpermute_b32 v71, v178, v69
	v_mul_f32_e32 v82, 0x3fb8aa3b, v82
	v_exp_f32_e32 v85, v82
	v_sub_f32_e32 v82, v120, v68
	v_mul_f32_e32 v82, 0x3fb8aa3b, v82
	s_waitcnt lgkmcnt(0)
	v_max3_f32 v69, v203, v69, v71
	v_sub_f32_e32 v74, v110, v69
	v_mul_f32_e32 v74, 0x3fb8aa3b, v74
	v_exp_f32_e32 v87, v82
	v_sub_f32_e32 v82, v104, v68
	v_exp_f32_e32 v104, v74
	v_sub_f32_e32 v74, v106, v69
	v_mul_f32_e32 v74, 0x3fb8aa3b, v74
	v_mul_f32_e32 v82, 0x3fb8aa3b, v82
	v_exp_f32_e32 v106, v74
	v_sub_f32_e32 v74, v112, v69
	v_exp_f32_e32 v89, v82
	v_sub_f32_e32 v82, v103, v68
	v_mul_f32_e32 v74, 0x3fb8aa3b, v74
	v_mul_f32_e32 v82, 0x3fb8aa3b, v82
	v_exp_f32_e32 v108, v74
	v_sub_f32_e32 v74, v114, v69
	v_sub_f32_e32 v81, v123, v68
	v_exp_f32_e32 v91, v82
	v_sub_f32_e32 v82, v102, v68
	v_sub_f32_e32 v72, 0xf149f2ca, v69
	v_mul_f32_e32 v74, 0x3fb8aa3b, v74
	v_mul_f32_e32 v81, 0x3fb8aa3b, v81
	v_mul_f32_e32 v82, 0x3fb8aa3b, v82
	v_mul_f32_e32 v72, 0x3fb8aa3b, v72
	v_exp_f32_e32 v110, v74
	v_sub_f32_e32 v74, v124, v69
	v_exp_f32_e32 v81, v81
	v_exp_f32_e32 v93, v82
	v_sub_f32_e32 v82, v101, v68
	v_exp_f32_e32 v80, v72
	v_mul_f32_e32 v74, 0x3fb8aa3b, v74
	v_mul_f32_e32 v82, 0x3fb8aa3b, v82
	v_exp_f32_e32 v112, v74
	v_sub_f32_e32 v74, v125, v69
	v_exp_f32_e32 v95, v82
	v_sub_f32_e32 v82, v100, v68
	v_sub_f32_e32 v73, v73, v68
	v_mul_f32_e32 v74, 0x3fb8aa3b, v74
	v_mul_f32_e32 v82, 0x3fb8aa3b, v82
	v_mul_f32_e32 v73, 0x3fb8aa3b, v73
	v_exp_f32_e32 v114, v74
	v_sub_f32_e32 v74, v126, v69
	v_exp_f32_e32 v97, v82
	v_exp_f32_e32 v107, v73
	v_pk_add_f32 v[72:73], v[80:81], 0 op_sel_hi:[1,0]
	v_mov_b32_e32 v82, v80
	v_mul_f32_e32 v74, 0x3fb8aa3b, v74
	v_pk_add_f32 v[72:73], v[82:83], v[72:73]
	v_mov_b32_e32 v84, v80
	v_exp_f32_e32 v116, v74
	v_sub_f32_e32 v74, v127, v69
	v_pk_add_f32 v[72:73], v[84:85], v[72:73]
	v_mov_b32_e32 v86, v80
	v_mul_f32_e32 v74, 0x3fb8aa3b, v74
	v_sub_f32_e32 v79, v79, v68
	v_pk_add_f32 v[72:73], v[86:87], v[72:73]
	v_mov_b32_e32 v88, v80
	v_exp_f32_e32 v118, v74
	v_sub_f32_e32 v74, v128, v69
	v_mul_f32_e32 v79, 0x3fb8aa3b, v79
	v_sub_f32_e32 v78, v78, v68
	v_pk_add_f32 v[72:73], v[88:89], v[72:73]
	v_mov_b32_e32 v90, v80
	v_mul_f32_e32 v74, 0x3fb8aa3b, v74
	v_exp_f32_e32 v99, v79
	v_mul_f32_e32 v78, 0x3fb8aa3b, v78
	v_sub_f32_e32 v77, v77, v68
	v_pk_add_f32 v[72:73], v[90:91], v[72:73]
	v_mov_b32_e32 v92, v80
	v_exp_f32_e32 v120, v74
	v_sub_f32_e32 v74, v129, v69
	v_exp_f32_e32 v101, v78
; #define LAS __attribute__((address_space(3)))
; #define MFMA32(a, b, c) __builtin_amdgcn_mfma_f32_32x32x16_bf16((a), (b), (c), 0, 0, 0)
; DI int tsw(int row) { return ((row >> 4) & 3) << 3; }
; DI void pv_accum(const f32x16 (&acc)[2][2], f32x16 (&o)[2][2], const LAS bf16_t* Vt, int lane) {
;     const int r = lane & 31, hh = lane >> 5;
; #pragma unroll
;     for (int mt = 0; mt < 2; ++mt) {
;         {   const bf16x8 p0 = pack8<0>(acc[mt][0]), p1 = pack8<0>(acc[mt][1]);
; #pragma unroll
;             for (int mo = 0; mo < 2; ++mo) { const LAS bf16_t* s = Vt + (32 * mo + r) * TLD; const int c0 = (32 * mt + 4 * hh) ^ tsw(32 * mo + r);
;                 const u32x2 lo = *(const LAS u32x2*)(s + c0), hi = *(const LAS u32x2*)(s + (c0 ^ 8)); u32x4 w; w.x = lo.x; w.y = lo.y; w.z = hi.x; w.w = hi.y; const bf16x8 vf = __builtin_bit_cast(bf16x8, w);
;                 o[mo][0] = MFMA32(vf, p0, o[mo][0]); o[mo][1] = MFMA32(vf, p1, o[mo][1]); } }
;         {   const bf16x8 p0 = pack8<1>(acc[mt][0]), p1 = pack8<1>(acc[mt][1]);
; #pragma unroll
;             for (int mo = 0; mo < 2; ++mo) { const LAS bf16_t* s = Vt + (32 * mo + r) * TLD; const int c0 = (32 * mt + 16 + 4 * hh) ^ tsw(32 * mo + r);
;                 const u32x2 lo = *(const LAS u32x2*)(s + c0), hi = *(const LAS u32x2*)(s + (c0 ^ 8)); u32x4 w; w.x = lo.x; w.y = lo.y; w.z = hi.x; w.w = hi.y; const bf16x8 vf = __builtin_bit_cast(bf16x8, w);
;                 o[mo][0] = MFMA32(vf, p0, o[mo][0]); o[mo][1] = MFMA32(vf, p1, o[mo][1]); } }
;     }
; DI void osm_update(f32x16 (&acc)[2][2], f32x16 (&o)[2][2], float (&m)[2], float (&l)[2]) {
;     ...
;         const float mn = fmaxf(m[nt], mx), sc = __expf(m[nt] - mn); float sm = 0.f;
; #pragma unroll
;         for (int mt = 0; mt < 2; ++mt)
; #pragma unroll
;             for (int g = 0; g < 16; ++g) { const float pz = __expf(acc[mt][nt][g] - mn); acc[mt][nt][g] = pz; sm += pz; }
;         sm += __shfl_xor(sm, 32);
;         l[nt] = l[nt] * sc + sm; m[nt] = mn;
; #pragma unroll
;         for (int g = 0; g < 16; ++g) { o[0][nt][g] *= sc; o[1][nt][g] *= sc; } }
	v_mul_f32_e32 v77, 0x3fb8aa3b, v77
	v_sub_f32_e32 v75, v75, v68
	v_pk_add_f32 v[72:73], v[92:93], v[72:73]
	v_mov_b32_e32 v94, v80
	v_mul_f32_e32 v74, 0x3fb8aa3b, v74
	v_exp_f32_e32 v103, v77
	v_mul_f32_e32 v75, 0x3fb8aa3b, v75
	v_pk_add_f32 v[72:73], v[94:95], v[72:73]
	v_mov_b32_e32 v96, v80
	v_exp_f32_e32 v122, v74
	v_sub_f32_e32 v74, v130, v69
	v_exp_f32_e32 v105, v75
	v_pk_add_f32 v[72:73], v[96:97], v[72:73]
	v_mov_b32_e32 v98, v80
	v_mul_f32_e32 v74, 0x3fb8aa3b, v74
	v_pk_add_f32 v[72:73], v[98:99], v[72:73]
	v_mov_b32_e32 v100, v80
	v_exp_f32_e32 v124, v74
	v_sub_f32_e32 v74, v131, v69
	v_pk_add_f32 v[72:73], v[100:101], v[72:73]
	v_mov_b32_e32 v102, v80
	v_mul_f32_e32 v74, 0x3fb8aa3b, v74
	v_pk_add_f32 v[72:73], v[102:103], v[72:73]
	v_exp_f32_e32 v126, v74
	v_sub_f32_e32 v74, v164, v69
	v_pk_add_f32 v[72:73], v[104:105], v[72:73]
	v_mul_f32_e32 v74, 0x3fb8aa3b, v74
	v_pk_add_f32 v[72:73], v[106:107], v[72:73]
	v_exp_f32_e32 v128, v74
	v_sub_f32_e32 v74, v165, v69
	v_pk_add_f32 v[72:73], v[108:109], v[72:73]
	v_mul_f32_e32 v74, 0x3fb8aa3b, v74
	v_pk_add_f32 v[72:73], v[110:111], v[72:73]
	v_exp_f32_e32 v130, v74
	v_sub_f32_e32 v74, v166, v69
	v_pk_add_f32 v[72:73], v[112:113], v[72:73]
	v_mul_f32_e32 v74, 0x3fb8aa3b, v74
	v_pk_add_f32 v[72:73], v[114:115], v[72:73]
	v_exp_f32_e32 v164, v74
	v_sub_f32_e32 v74, v167, v69
	v_pk_add_f32 v[72:73], v[116:117], v[72:73]
	v_mul_f32_e32 v74, 0x3fb8aa3b, v74
	v_pk_add_f32 v[72:73], v[118:119], v[72:73]
	v_exp_f32_e32 v166, v74
	v_sub_f32_e32 v74, v168, v69
	v_pk_add_f32 v[72:73], v[120:121], v[72:73]
	v_mov_b32_e32 v123, v121
	v_mul_f32_e32 v74, 0x3fb8aa3b, v74
	v_pk_add_f32 v[72:73], v[122:123], v[72:73]
	v_mov_b32_e32 v125, v121
	v_exp_f32_e32 v168, v74
	v_sub_f32_e32 v74, v169, v69
	v_pk_add_f32 v[72:73], v[124:125], v[72:73]
	v_mul_f32_e32 v74, 0x3fb8aa3b, v74
	v_mov_b32_e32 v127, v121
	v_exp_f32_e32 v170, v74
	v_sub_f32_e32 v74, v171, v69
	v_pk_add_f32 v[72:73], v[126:127], v[72:73]
	v_mov_b32_e32 v129, v121
	v_mul_f32_e32 v74, 0x3fb8aa3b, v74
	v_pk_add_f32 v[72:73], v[128:129], v[72:73]
	v_mov_b32_e32 v131, v121
	v_exp_f32_e32 v172, v74
	v_sub_f32_e32 v74, v173, v69
	v_pk_add_f32 v[72:73], v[130:131], v[72:73]
	v_mov_b32_e32 v165, v121
	v_mul_f32_e32 v74, 0x3fb8aa3b, v74
	v_pk_add_f32 v[72:73], v[164:165], v[72:73]
	v_mov_b32_e32 v167, v121
	v_exp_f32_e32 v174, v74
	v_pk_add_f32 v[72:73], v[166:167], v[72:73]
	v_mov_b32_e32 v169, v121
	v_pk_add_f32 v[72:73], v[168:169], v[72:73]
	v_mov_b32_e32 v171, v121
	v_pk_add_f32 v[72:73], v[170:171], v[72:73]
	v_mov_b32_e32 v173, v121
	v_pk_add_f32 v[72:73], v[172:173], v[72:73]
	v_mov_b32_e32 v175, v121
	v_pk_add_f32 v[72:73], v[174:175], v[72:73]
	v_sub_f32_e32 v71, v203, v69
	ds_bpermute_b32 v77, v178, v73
	ds_bpermute_b32 v76, v178, v72
	v_mul_f32_e32 v71, 0x3fb8aa3b, v71
	v_exp_f32_e32 v74, v71
	v_mov_b32_e32 v75, v70
	v_cvt_pk_bf16_f32 v70, v81, v83
	s_waitcnt lgkmcnt(0)
	v_pk_add_f32 v[72:73], v[72:73], v[76:77]
	v_pk_mul_f32 v[50:51], v[50:51], v[74:75] op_sel_hi:[1,0]
	v_pk_fma_f32 v[206:207], v[206:207], v[74:75], v[72:73]
	v_pk_mul_f32 v[48:49], v[48:49], v[74:75] op_sel_hi:[1,0]
	v_pk_mul_f32 v[46:47], v[46:47], v[74:75] op_sel_hi:[1,0]
	v_pk_mul_f32 v[44:45], v[44:45], v[74:75] op_sel_hi:[1,0]
	v_pk_mul_f32 v[42:43], v[42:43], v[74:75] op_sel_hi:[1,0]
	v_pk_mul_f32 v[40:41], v[40:41], v[74:75] op_sel_hi:[1,0]
	v_pk_mul_f32 v[38:39], v[38:39], v[74:75] op_sel_hi:[1,0]
	v_pk_mul_f32 v[36:37], v[36:37], v[74:75] op_sel_hi:[1,0]
	v_pk_mul_f32 v[18:19], v[18:19], v[74:75] op_sel_hi:[1,0]
	v_pk_mul_f32 v[16:17], v[16:17], v[74:75] op_sel_hi:[1,0]
	v_pk_mul_f32 v[14:15], v[14:15], v[74:75] op_sel_hi:[1,0]
	v_pk_mul_f32 v[12:13], v[12:13], v[74:75] op_sel_hi:[1,0]
	v_pk_mul_f32 v[10:11], v[10:11], v[74:75] op_sel_hi:[1,0]
	v_pk_mul_f32 v[8:9], v[8:9], v[74:75] op_sel_hi:[1,0]
	v_pk_mul_f32 v[6:7], v[6:7], v[74:75] op_sel_hi:[1,0]
	v_pk_mul_f32 v[4:5], v[4:5], v[74:75] op_sel_hi:[1,0]
	v_cvt_pk_bf16_f32 v71, v85, v87
	v_cvt_pk_bf16_f32 v74, v80, v80
	ds_read2_b64 v[78:81], v228 offset1:4
	ds_read_b64 v[84:85], v229
	v_cvt_pk_bf16_f32 v72, v89, v91
	v_cvt_pk_bf16_f32 v73, v93, v95
	v_mov_b32_e32 v75, v74
	s_waitcnt lgkmcnt(1)
	v_mov_b32_e32 v82, v78
	v_mov_b32_e32 v83, v79
	v_mov_b32_e32 v76, v74
	v_mov_b32_e32 v77, v74
	s_waitcnt lgkmcnt(0)
	v_mfma_f32_32x32x16_bf16 v[52:67], v[82:85], v[70:73], v[52:67]
	s_addk_i32 s4, 0x80
	s_cmpk_lg_i32 s4, 0x400
	v_mov_b32_e32 v203, v69
	v_mov_b32_e32 v245, v68
	v_mfma_f32_32x32x16_bf16 v[36:51], v[82:85], v[74:77], v[36:51]
	ds_read2_b64 v[82:85], v230 offset1:8
	ds_read_b64 v[88:89], v231
	s_waitcnt lgkmcnt(1)
	v_mov_b32_e32 v86, v82
	v_mov_b32_e32 v87, v83
	s_waitcnt lgkmcnt(0)
	s_nop 0
	v_mfma_f32_32x32x16_bf16 v[20:35], v[86:89], v[70:73], v[20:35]
	v_cvt_pk_bf16_f32 v70, v97, v99
	v_cvt_pk_bf16_f32 v71, v101, v103
	v_cvt_pk_bf16_f32 v72, v105, v107
	v_cvt_pk_bf16_f32 v73, v109, v111
	v_mfma_f32_32x32x16_bf16 v[4:19], v[86:89], v[74:77], v[4:19]
	ds_read2_b64 v[86:89], v228 offset0:8 offset1:12
	ds_read_b64 v[82:83], v232
	v_cvt_pk_bf16_f32 v76, v104, v106
	v_cvt_pk_bf16_f32 v77, v108, v110
	s_waitcnt lgkmcnt(0)
	v_mfma_f32_32x32x16_bf16 v[52:67], v[80:83], v[70:73], v[52:67]
	v_mfma_f32_32x32x16_bf16 v[36:51], v[80:83], v[74:77], v[36:51]
	ds_read_b64 v[78:79], v233
	ds_read_b64 v[80:81], v234
	s_waitcnt lgkmcnt(0)
	v_mfma_f32_32x32x16_bf16 v[20:35], v[78:81], v[70:73], v[20:35]
	v_cvt_pk_bf16_f32 v72, v121, v121
	v_cvt_pk_bf16_f32 v70, v113, v115
	v_cvt_pk_bf16_f32 v71, v117, v119
	v_mov_b32_e32 v73, v72
	v_mfma_f32_32x32x16_bf16 v[4:19], v[78:81], v[74:77], v[4:19]
	ds_read_b64 v[80:81], v235
	v_mov_b32_e32 v78, v86
	v_mov_b32_e32 v79, v87
	v_cvt_pk_bf16_f32 v74, v112, v114
	v_cvt_pk_bf16_f32 v75, v116, v118
	v_cvt_pk_bf16_f32 v76, v120, v122
	v_cvt_pk_bf16_f32 v77, v124, v126
	s_waitcnt lgkmcnt(0)
	v_mfma_f32_32x32x16_bf16 v[52:67], v[78:81], v[70:73], v[52:67]
	v_mfma_f32_32x32x16_bf16 v[36:51], v[78:81], v[74:77], v[36:51]
	ds_read_b64 v[80:81], v236
	v_mov_b32_e32 v78, v84
	v_mov_b32_e32 v79, v85
	s_waitcnt lgkmcnt(0)
	s_nop 0
	v_mfma_f32_32x32x16_bf16 v[20:35], v[78:81], v[70:73], v[20:35]
	v_mov_b32_e32 v70, v72
	v_mov_b32_e32 v71, v72
	v_mfma_f32_32x32x16_bf16 v[4:19], v[78:81], v[74:77], v[4:19]
	ds_read_b64 v[80:81], v237
	v_mov_b32_e32 v78, v88
	v_mov_b32_e32 v79, v89
	v_cvt_pk_bf16_f32 v74, v128, v130
	v_cvt_pk_bf16_f32 v75, v164, v166
	v_cvt_pk_bf16_f32 v76, v168, v170
	v_cvt_pk_bf16_f32 v77, v172, v174
	s_waitcnt lgkmcnt(0)
	v_mfma_f32_32x32x16_bf16 v[52:67], v[78:81], v[70:73], v[52:67]
	v_mfma_f32_32x32x16_bf16 v[36:51], v[78:81], v[74:77], v[36:51]
	ds_read_b64 v[78:79], v238
	ds_read_b64 v[80:81], v239
	s_waitcnt lgkmcnt(0)
	v_mfma_f32_32x32x16_bf16 v[20:35], v[78:81], v[70:73], v[20:35]
	v_mfma_f32_32x32x16_bf16 v[4:19], v[78:81], v[74:77], v[4:19]
	s_cbranch_scc1 .LBB0_661
; #define LAS __attribute__((address_space(3)))
; DI unsigned pk2(float lo, float hi) { f32x2 v = {lo, hi}; bf16x2v b = __builtin_convertvector(v, bf16x2v); return __builtin_bit_cast(unsigned, b); }
; DI float frcp(float x) { return __builtin_amdgcn_rcpf(x); }
; template <class F> DI void store_o_rows(LAS bf16_t* T, const f32x16 (&o)[2][2], const float (&scale)[2], int lane, F rowp) {
;     const int r = lane & 31, hh = lane >> 5;
; #pragma unroll
;     for (int mo = 0; mo < 2; ++mo)
; #pragma unroll
;         for (int nt = 0; nt < 2; ++nt)
; #pragma unroll
;             for (int g = 0; g < 4; ++g) { u32x2 w; w.x = pk2(o[mo][nt][4 * g] * scale[nt], o[mo][nt][4 * g + 1] * scale[nt]); w.y = pk2(o[mo][nt][4 * g + 2] * scale[nt], o[mo][nt][4 * g + 3] * scale[nt]);
;                 *(LAS u32x2*)(T + (32 * nt + r) * TLD + 32 * mo + 8 * g + 4 * hh) = w; }
;     asm volatile("s_waitcnt lgkmcnt(0)" ::: "memory");
; #pragma unroll
;     for (int it = 0; it < 8; ++it) { const int id = it * 64 + lane, q = id >> 3, part = id & 7; *(u32x4*)(rowp(q) + 8 * part) = *(const LAS u32x4*)(T + q * TLD + 8 * part); }
;     asm volatile("s_waitcnt lgkmcnt(0)" ::: "memory");
; }
; DI void na_wave_unit(KArgs args, LAS unsigned char* L, const Ctx& c, int u, int lane, int wave) {
;     ...
;     asm volatile("s_waitcnt lgkmcnt(0)" ::: "memory");
;     const float sc[2] = {frcp(ls[0]), frcp(ls[1])};
;     store_o_rows(Vt, o, sc, lane, [&](int q) { return BIGP(bf16_t, B_ONA) + (tq0 + q) * 768 + 64 * head; });
	v_rcp_f32_e32 v68, v207
	v_rcp_f32_e32 v70, v206
	s_waitcnt lgkmcnt(0)
	v_readlane_b32 s0, v254, 42
	s_nop 1
	v_pk_mul_f32 v[52:53], v[52:53], v[68:69] op_sel_hi:[1,0]
	v_pk_mul_f32 v[54:55], v[54:55], v[68:69] op_sel_hi:[1,0]
	v_cvt_pk_bf16_f32 v52, v52, v53
	v_cvt_pk_bf16_f32 v53, v54, v55
	v_pk_mul_f32 v[54:55], v[56:57], v[68:69] op_sel_hi:[1,0]
	v_pk_mul_f32 v[56:57], v[58:59], v[68:69] op_sel_hi:[1,0]
	v_cvt_pk_bf16_f32 v54, v54, v55
	v_cvt_pk_bf16_f32 v55, v56, v57
	ds_write2_b64 v242, v[52:53], v[54:55] offset1:2
	v_pk_mul_f32 v[52:53], v[60:61], v[68:69] op_sel_hi:[1,0]
	v_pk_mul_f32 v[54:55], v[62:63], v[68:69] op_sel_hi:[1,0]
	v_pk_mul_f32 v[36:37], v[36:37], v[70:71] op_sel_hi:[1,0]
	v_pk_mul_f32 v[38:39], v[38:39], v[70:71] op_sel_hi:[1,0]
	v_cvt_pk_bf16_f32 v52, v52, v53
	v_cvt_pk_bf16_f32 v53, v54, v55
	v_pk_mul_f32 v[54:55], v[64:65], v[68:69] op_sel_hi:[1,0]
	v_pk_mul_f32 v[56:57], v[66:67], v[68:69] op_sel_hi:[1,0]
	v_cvt_pk_bf16_f32 v36, v36, v37
	v_cvt_pk_bf16_f32 v37, v38, v39
	v_pk_mul_f32 v[38:39], v[40:41], v[70:71] op_sel_hi:[1,0]
	v_pk_mul_f32 v[40:41], v[42:43], v[70:71] op_sel_hi:[1,0]
	v_cvt_pk_bf16_f32 v54, v54, v55
	v_cvt_pk_bf16_f32 v55, v56, v57
	v_cvt_pk_bf16_f32 v38, v38, v39
	v_cvt_pk_bf16_f32 v39, v40, v41
	ds_write2_b64 v242, v[52:53], v[54:55] offset0:4 offset1:6
	ds_write2_b64 v243, v[36:37], v[38:39] offset1:2
	v_pk_mul_f32 v[36:37], v[44:45], v[70:71] op_sel_hi:[1,0]
	v_pk_mul_f32 v[38:39], v[46:47], v[70:71] op_sel_hi:[1,0]
	v_pk_mul_f32 v[20:21], v[20:21], v[68:69] op_sel_hi:[1,0]
	v_pk_mul_f32 v[22:23], v[22:23], v[68:69] op_sel_hi:[1,0]
	v_cvt_pk_bf16_f32 v36, v36, v37
	v_cvt_pk_bf16_f32 v37, v38, v39
	v_pk_mul_f32 v[38:39], v[48:49], v[70:71] op_sel_hi:[1,0]
	v_pk_mul_f32 v[40:41], v[50:51], v[70:71] op_sel_hi:[1,0]
	v_cvt_pk_bf16_f32 v20, v20, v21
	v_cvt_pk_bf16_f32 v21, v22, v23
	v_pk_mul_f32 v[22:23], v[24:25], v[68:69] op_sel_hi:[1,0]
	v_pk_mul_f32 v[24:25], v[26:27], v[68:69] op_sel_hi:[1,0]
	v_cvt_pk_bf16_f32 v38, v38, v39
	v_cvt_pk_bf16_f32 v39, v40, v41
	v_cvt_pk_bf16_f32 v22, v22, v23
	v_cvt_pk_bf16_f32 v23, v24, v25
	ds_write2_b64 v243, v[36:37], v[38:39] offset0:4 offset1:6
	ds_write2_b64 v242, v[20:21], v[22:23] offset0:8 offset1:10
	v_pk_mul_f32 v[20:21], v[28:29], v[68:69] op_sel_hi:[1,0]
	v_pk_mul_f32 v[22:23], v[30:31], v[68:69] op_sel_hi:[1,0]
	v_pk_mul_f32 v[4:5], v[4:5], v[70:71] op_sel_hi:[1,0]
	v_pk_mul_f32 v[6:7], v[6:7], v[70:71] op_sel_hi:[1,0]
	v_cvt_pk_bf16_f32 v20, v20, v21
	v_cvt_pk_bf16_f32 v21, v22, v23
	v_pk_mul_f32 v[22:23], v[32:33], v[68:69] op_sel_hi:[1,0]
	v_pk_mul_f32 v[24:25], v[34:35], v[68:69] op_sel_hi:[1,0]
	v_cvt_pk_bf16_f32 v4, v4, v5
	v_cvt_pk_bf16_f32 v5, v6, v7
	v_pk_mul_f32 v[6:7], v[8:9], v[70:71] op_sel_hi:[1,0]
	v_pk_mul_f32 v[8:9], v[10:11], v[70:71] op_sel_hi:[1,0]
	v_cvt_pk_bf16_f32 v22, v22, v23
	v_cvt_pk_bf16_f32 v23, v24, v25
	v_cvt_pk_bf16_f32 v6, v6, v7
	v_cvt_pk_bf16_f32 v7, v8, v9
	ds_write2_b64 v242, v[20:21], v[22:23] offset0:12 offset1:14
	ds_write2_b64 v243, v[4:5], v[6:7] offset0:8 offset1:10
	v_pk_mul_f32 v[4:5], v[12:13], v[70:71] op_sel_hi:[1,0]
	v_pk_mul_f32 v[6:7], v[14:15], v[70:71] op_sel_hi:[1,0]
	v_cvt_pk_bf16_f32 v4, v4, v5
	v_cvt_pk_bf16_f32 v5, v6, v7
	v_pk_mul_f32 v[6:7], v[16:17], v[70:71] op_sel_hi:[1,0]
	v_pk_mul_f32 v[8:9], v[18:19], v[70:71] op_sel_hi:[1,0]
	v_cvt_pk_bf16_f32 v6, v6, v7
	v_cvt_pk_bf16_f32 v7, v8, v9
	ds_write2_b64 v243, v[4:5], v[6:7] offset0:12 offset1:14
	s_waitcnt lgkmcnt(0)
	v_readlane_b32 s4, v254, 56
	v_readlane_b32 s1, v254, 43
	ds_read_b128 v[4:7], v244
	v_or_b32_e32 v8, s4, v182
	v_mov_b64_e32 v[12:13], s[0:1]
	s_movk_i32 s0, 0x600
	v_mad_u64_u32 v[8:9], s[2:3], v8, s0, v[12:13]
	v_readlane_b32 s1, v254, 58
	v_mov_b32_e32 v203, v3
	s_movk_i32 s33, 0x600
	v_mad_u32_u24 v9, s1, v225, v9
	v_lshl_add_u64 v[8:9], v[8:9], 0, s[92:93]
	v_lshl_add_u64 v[14:15], v[8:9], 0, v[202:203]
	ds_read_b128 v[8:11], v244 offset:1152
	s_waitcnt lgkmcnt(1)
	global_store_dwordx4 v[14:15], v[4:7], off
	s_nop 1
	v_or_b32_e32 v4, s4, v184
	v_mad_u64_u32 v[4:5], s[2:3], v4, s0, v[12:13]
	v_mad_u32_u24 v5, s1, v225, v5
	v_lshl_add_u64 v[4:5], v[4:5], 0, s[92:93]
	v_lshl_add_u64 v[4:5], v[4:5], 0, v[202:203]
	s_waitcnt lgkmcnt(0)
	global_store_dwordx4 v[4:5], v[8:11], off
	ds_read_b128 v[4:7], v244 offset:2304
	s_nop 0
	v_or_b32_e32 v8, s4, v186
	v_mad_u64_u32 v[8:9], s[2:3], v8, s0, v[12:13]
	v_mad_u32_u24 v9, s1, v225, v9
	v_lshl_add_u64 v[8:9], v[8:9], 0, s[92:93]
	v_lshl_add_u64 v[14:15], v[8:9], 0, v[202:203]
	ds_read_b128 v[8:11], v244 offset:3456
	s_waitcnt lgkmcnt(1)
	global_store_dwordx4 v[14:15], v[4:7], off
	s_nop 1
	v_or_b32_e32 v4, s4, v188
	v_mad_u64_u32 v[4:5], s[2:3], v4, s0, v[12:13]
	v_mad_u32_u24 v5, s1, v225, v5
	v_lshl_add_u64 v[4:5], v[4:5], 0, s[92:93]
	v_lshl_add_u64 v[4:5], v[4:5], 0, v[202:203]
	s_waitcnt lgkmcnt(0)
	global_store_dwordx4 v[4:5], v[8:11], off
	ds_read_b128 v[4:7], v244 offset:4608
	s_nop 0
	v_or_b32_e32 v8, s4, v190
	v_mad_u64_u32 v[8:9], s[2:3], v8, s0, v[12:13]
	v_mad_u32_u24 v9, s1, v225, v9
	v_lshl_add_u64 v[8:9], v[8:9], 0, s[92:93]
	v_lshl_add_u64 v[14:15], v[8:9], 0, v[202:203]
	ds_read_b128 v[8:11], v244 offset:5760
	s_waitcnt lgkmcnt(1)
	global_store_dwordx4 v[14:15], v[4:7], off
	s_nop 1
	v_or_b32_e32 v4, s4, v192
	v_mad_u64_u32 v[4:5], s[2:3], v4, s0, v[12:13]
	v_mad_u32_u24 v5, s1, v225, v5
	v_lshl_add_u64 v[4:5], v[4:5], 0, s[92:93]
	v_lshl_add_u64 v[4:5], v[4:5], 0, v[202:203]
	s_waitcnt lgkmcnt(0)
	global_store_dwordx4 v[4:5], v[8:11], off
	ds_read_b128 v[4:7], v244 offset:6912
	s_nop 0
	v_or_b32_e32 v8, s4, v194
	v_mad_u64_u32 v[8:9], s[2:3], v8, s0, v[12:13]
	v_mad_u32_u24 v9, s1, v225, v9
	v_lshl_add_u64 v[8:9], v[8:9], 0, s[92:93]
	v_lshl_add_u64 v[14:15], v[8:9], 0, v[202:203]
	ds_read_b128 v[8:11], v244 offset:8064
	s_waitcnt lgkmcnt(1)
	global_store_dwordx4 v[14:15], v[4:7], off
	s_nop 1
	v_or_b32_e32 v4, s4, v196
	v_mad_u64_u32 v[4:5], s[2:3], v4, s0, v[12:13]
	v_mad_u32_u24 v5, s1, v225, v5
	v_lshl_add_u64 v[4:5], v[4:5], 0, s[92:93]
	v_lshl_add_u64 v[4:5], v[4:5], 0, v[202:203]
	s_waitcnt lgkmcnt(0)
	global_store_dwordx4 v[4:5], v[8:11], off
	s_waitcnt lgkmcnt(0)
	v_readlane_b32 s0, v255, 63
	s_nop 1
	s_cmp_lg_u32 s0, 0
	s_cselect_b64 s[0:1], -1, 0
	s_branch .LBB0_652
